# RG-LRU stage-4 cross-segment carry: seven exec-masked serial LDS round trips -> all (P,H) pairs read up front, carry advanced with fma + v_cndmask under the same lane masks
# baseline (speedup 1.0000x reference)
; __device__ __forceinline__ float bf2f(bf16_t v) { return __uint_as_float(((unsigned)v) << 16); }
; __device__ __forceinline__ float sigmoidf_(float x) { return __builtin_amdgcn_rcpf(1.f + __expf(-x)); }
; #define MFMA16(a, b, c) __builtin_amdgcn_mfma_f32_16x16x32_bf16((a), (b), (c), 0, 0, 0)
; __device__ __forceinline__ void rglru_unit(const Params& p, const WS& ws, int j, int u, bool dry = false) {
;     ...
;       for (int ks = 0; ks < 4; ++ks) {
;         const bf16x8 xf = *(const bf16x8*)(XC + (16 * w + lr) * 136 + 32 * ks + 8 * lq);
; #pragma unroll
;         for (int gate = 0; gate < 2; ++gate)
; #pragma unroll
;           for (int mt = 0; mt < 2; ++mt) {
;             const bf16x8 wf = *(const bf16x8*)(WG + (gate * 32 + 16 * mt + lr) * 136 + 32 * ks + 8 * lq);
;             ga_[gate][mt] = MFMA16(wf, xf, ga_[gate][mt]);
;           }
;       }
;       const int tok = 16 * w + lr;
; #pragma unroll
;       for (int mt = 0; mt < 2; ++mt)
; #pragma unroll
;         for (int jj = 0; jj < 4; ++jj) {
;           const int n = 16 * mt + 4 * lq + jj;
;           const float xcv = bf2f(XC[tok * 136 + 32 * jq + n]);
;           const float r = sigmoidf_(ga_[0][mt][jj] + ba[mt][jj]);
;           const float ig = sigmoidf_(ga_[1][mt][jj] + bx[mt][jj]);
;           const float la = -r * sp[mt][jj];
;           const float a = __expf(la);
;           const float x2 = 2.f * la;
;           const float om = x2 > -0.02f ? -x2 * (1.f + 0.5f * x2 * (1.f + x2 * (1.f / 3.f))) : 1.f - a * a;
;           const float mult = __builtin_amdgcn_sqrtf(fmaxf(om, 0.f));
;           AUa[tok * 33 + n] = a;
;           AUu[tok * 33 + n] = mult * ig * xcv;
;         }
.LBB0_1420:
	ds_read_b128 v[52:55], v111
	ds_read_b128 v[56:59], v112 offset:17408
	ds_read_b128 v[60:63], v112 offset:21760
	ds_read_b128 v[64:67], v112 offset:26112
	ds_read_b128 v[136:139], v112 offset:30464
	ds_read_b128 v[212:215], v111 offset:64
	ds_read_b128 v[216:219], v111 offset:128
	ds_read_b128 v[220:223], v111 offset:192
	ds_read_b128 v[224:227], v112 offset:17472
	ds_read_b128 v[228:231], v112 offset:21824
	ds_read_b128 v[232:235], v112 offset:26176
	ds_read_b128 v[244:247], v112 offset:30528
	ds_read_b128 v[248:251], v112 offset:17536
	ds_read_b128 v[252:255], v112 offset:21888
	s_waitcnt lgkmcnt(12)
	v_mfma_f32_16x16x32_bf16 v[56:59], v[56:59], v[52:55], 0
	s_waitcnt lgkmcnt(11)
	v_mfma_f32_16x16x32_bf16 v[60:63], v[60:63], v[52:55], 0
	s_waitcnt lgkmcnt(10)
	v_mfma_f32_16x16x32_bf16 v[64:67], v[64:67], v[52:55], 0
	s_waitcnt lgkmcnt(9)
	v_mfma_f32_16x16x32_bf16 v[52:55], v[136:139], v[52:55], 0
	s_nop 0
	s_nop 0
	s_waitcnt lgkmcnt(5)
	v_mfma_f32_16x16x32_bf16 v[56:59], v[224:227], v[212:215], v[56:59]
	ds_read_b128 v[224:227], v112 offset:26240
	s_nop 0
	s_waitcnt lgkmcnt(5)
	v_mfma_f32_16x16x32_bf16 v[60:63], v[228:231], v[212:215], v[60:63]
	ds_read_b128 v[228:231], v112 offset:30592
	s_nop 0
	s_waitcnt lgkmcnt(5)
	v_mfma_f32_16x16x32_bf16 v[64:67], v[232:235], v[212:215], v[64:67]
	ds_read_b128 v[232:235], v112 offset:17600
	s_nop 0
	s_waitcnt lgkmcnt(5)
	v_mfma_f32_16x16x32_bf16 v[52:55], v[244:247], v[212:215], v[52:55]
	ds_read_b128 v[244:247], v112 offset:21952
	s_nop 0
	s_nop 0
	s_waitcnt lgkmcnt(5)
	v_mfma_f32_16x16x32_bf16 v[56:59], v[248:251], v[216:219], v[56:59]
	ds_read_b128 v[248:251], v112 offset:26304
	s_nop 0
	s_waitcnt lgkmcnt(5)
	v_mfma_f32_16x16x32_bf16 v[60:63], v[252:255], v[216:219], v[60:63]
	ds_read_b128 v[252:255], v112 offset:30656
	s_nop 0
	s_waitcnt lgkmcnt(5)
	v_mfma_f32_16x16x32_bf16 v[140:143], v[224:227], v[216:219], v[64:67]
	s_nop 2
	s_nop 0
	s_waitcnt lgkmcnt(4)
	v_mfma_f32_16x16x32_bf16 v[52:55], v[228:231], v[216:219], v[52:55]
	s_nop 0
	s_nop 0
	ds_read_u16 v13, v113
	s_waitcnt lgkmcnt(4)
	v_mfma_f32_16x16x32_bf16 v[64:67], v[232:235], v[220:223], v[56:59]
	s_nop 2
	s_nop 0
	s_waitcnt lgkmcnt(3)
	v_mfma_f32_16x16x32_bf16 v[56:59], v[244:247], v[220:223], v[60:63]
	s_nop 2
	s_nop 0
	v_add_f32_e32 v14, v0, v64
	v_mul_f32_e32 v14, 0xbfb8aa3b, v14
	v_exp_f32_e32 v14, v14
	s_waitcnt lgkmcnt(2)
	v_mfma_f32_16x16x32_bf16 v[60:63], v[248:251], v[220:223], v[140:143]
	s_nop 2
	s_nop 0
	v_add_f32_e32 v14, 1.0, v14
	v_rcp_f32_e64 v14, -v14
	s_waitcnt lgkmcnt(0)
	v_mfma_f32_16x16x32_bf16 v[52:55], v[252:255], v[220:223], v[52:55]
	v_mul_f32_e32 v14, v89, v14
	v_mul_f32_e32 v15, 0x3fb8aa3b, v14
	v_exp_f32_e32 v15, v15
	v_add_f32_e32 v14, v14, v14
	v_cmp_nlt_f32_e64 s[52:53], s29, v14
	s_and_saveexec_b64 s[4:5], s[52:53]
	s_xor_b64 s[4:5], exec, s[4:5]
	v_fma_f32 v64, -v15, v15, 1.0
	s_andn2_saveexec_b64 s[4:5], s[4:5]
	v_pk_mul_f32 v[136:137], v[14:15], s[88:89] op_sel_hi:[0,1]
	v_add_f32_e32 v64, 1.0, v137
	v_fma_f32 v64, v136, v64, 1.0
	v_mul_f32_e64 v64, v64, -v14
	s_or_b64 exec, exec, s[4:5]
	v_add_f32_e32 v14, v8, v60
	v_max_f32_e32 v60, v64, v64
	v_add_f32_e32 v64, v1, v65
	v_mul_f32_e32 v14, 0xbfb8aa3b, v14
	v_mul_f32_e32 v64, 0xbfb8aa3b, v64
	v_exp_f32_e32 v14, v14
	v_exp_f32_e32 v64, v64
	v_max_f32_e32 v60, 0, v60
	v_sqrt_f32_e32 v60, v60
	v_add_f32_e32 v14, 1.0, v14
	v_add_f32_e32 v64, 1.0, v64
	v_rcp_f32_e32 v14, v14
	v_rcp_f32_e64 v64, -v64
	v_lshlrev_b32_e32 v13, 16, v13
	v_mul_f32_e32 v14, v14, v60
	v_mul_f32_e32 v64, v93, v64
	v_mul_f32_e32 v14, v14, v13
	ds_read_u16 v60, v113 offset:2
	v_mul_f32_e32 v13, 0x3fb8aa3b, v64
	v_exp_f32_e32 v13, v13
	ds_write2st64_b32 v72, v15, v14 offset0:136 offset1:169
	v_add_f32_e32 v14, v64, v64
	v_cmp_nlt_f32_e64 s[52:53], s29, v14
	s_and_saveexec_b64 s[4:5], s[52:53]
	s_xor_b64 s[4:5], exec, s[4:5]
	v_fma_f32 v15, -v13, v13, 1.0
	s_andn2_saveexec_b64 s[4:5], s[4:5]
	v_pk_mul_f32 v[64:65], v[14:15], s[88:89] op_sel_hi:[0,1]
	v_add_f32_e32 v15, 1.0, v65
	v_fma_f32 v15, v64, v15, 1.0
	v_mul_f32_e64 v15, v15, -v14
	s_or_b64 exec, exec, s[4:5]
	s_waitcnt lgkmcnt(1)
	v_lshlrev_b32_e32 v14, 16, v60
	v_add_f32_e32 v60, v9, v61
	v_mul_f32_e32 v60, 0xbfb8aa3b, v60
	v_exp_f32_e32 v60, v60
	v_max_f32_e32 v15, v15, v15
	v_max_f32_e32 v15, 0, v15
	v_sqrt_f32_e32 v15, v15
	v_add_f32_e32 v60, 1.0, v60
	v_rcp_f32_e32 v60, v60
	v_add_u32_e32 v135, 4, v72
	v_mul_f32_e32 v15, v60, v15
	v_mul_f32_e32 v14, v15, v14
	ds_write2st64_b32 v135, v13, v14 offset0:136 offset1:169
	v_add_f32_e32 v14, v2, v66
	v_mul_f32_e32 v14, 0xbfb8aa3b, v14
	v_exp_f32_e32 v14, v14
	ds_read_u16 v13, v113 offset:4
	v_add_f32_e32 v14, 1.0, v14
	v_rcp_f32_e64 v14, -v14
	s_nop 0
	v_mul_f32_e32 v14, v95, v14
	v_mul_f32_e32 v15, 0x3fb8aa3b, v14
	v_exp_f32_e32 v15, v15
	v_add_f32_e32 v14, v14, v14
	v_cmp_nlt_f32_e64 s[52:53], s29, v14
	s_and_saveexec_b64 s[4:5], s[52:53]
	s_xor_b64 s[4:5], exec, s[4:5]
	v_fma_f32 v60, -v15, v15, 1.0
	s_andn2_saveexec_b64 s[4:5], s[4:5]
	v_pk_mul_f32 v[60:61], v[14:15], s[88:89] op_sel_hi:[0,1]
	v_add_f32_e32 v61, 1.0, v61
	v_fma_f32 v60, v60, v61, 1.0
	v_mul_f32_e64 v60, v60, -v14
	s_or_b64 exec, exec, s[4:5]
	v_add_f32_e32 v14, v10, v62
	v_mul_f32_e32 v14, 0xbfb8aa3b, v14
	v_exp_f32_e32 v14, v14
	v_max_f32_e32 v60, v60, v60
	v_max_f32_e32 v60, 0, v60
	v_sqrt_f32_e32 v60, v60
	v_add_f32_e32 v14, 1.0, v14
	v_rcp_f32_e32 v14, v14
	s_waitcnt lgkmcnt(0)
; __device__ __forceinline__ float bf2f(bf16_t v) { return __uint_as_float(((unsigned)v) << 16); }
; __device__ __forceinline__ float sigmoidf_(float x) { return __builtin_amdgcn_rcpf(1.f + __expf(-x)); }
; __device__ __forceinline__ void rglru_unit(const Params& p, const WS& ws, int j, int u, bool dry = false) {
;     ...
; #pragma unroll
;       for (int mt = 0; mt < 2; ++mt)
; #pragma unroll
;         for (int jj = 0; jj < 4; ++jj) {
;           const int n = 16 * mt + 4 * lq + jj;
;           const float xcv = bf2f(XC[tok * 136 + 32 * jq + n]);
;           const float r = sigmoidf_(ga_[0][mt][jj] + ba[mt][jj]);
;           const float ig = sigmoidf_(ga_[1][mt][jj] + bx[mt][jj]);
;           const float la = -r * sp[mt][jj];
;           const float a = __expf(la);
;           const float x2 = 2.f * la;
;           const float om = x2 > -0.02f ? -x2 * (1.f + 0.5f * x2 * (1.f + x2 * (1.f / 3.f))) : 1.f - a * a;
;           const float mult = __builtin_amdgcn_sqrtf(fmaxf(om, 0.f));
;           AUa[tok * 33 + n] = a;
;           AUu[tok * 33 + n] = mult * ig * xcv;
;         }
;     }
;     __syncthreads();
	v_lshlrev_b32_e32 v13, 16, v13
	v_add_u32_e32 v136, 8, v72
	v_mul_f32_e32 v14, v14, v60
	v_mul_f32_e32 v13, v14, v13
	v_add_f32_e32 v14, v3, v67
	v_mul_f32_e32 v14, 0xbfb8aa3b, v14
	v_exp_f32_e32 v14, v14
	ds_write2st64_b32 v136, v15, v13 offset0:136 offset1:169
	ds_read_u16 v13, v113 offset:6
	v_add_f32_e32 v14, 1.0, v14
	v_rcp_f32_e64 v14, -v14
	s_nop 0
	v_mul_f32_e32 v14, v96, v14
	v_mul_f32_e32 v15, 0x3fb8aa3b, v14
	v_exp_f32_e32 v15, v15
	v_add_f32_e32 v14, v14, v14
	v_cmp_nlt_f32_e64 s[52:53], s29, v14
	s_and_saveexec_b64 s[4:5], s[52:53]
	s_xor_b64 s[4:5], exec, s[4:5]
	v_fma_f32 v60, -v15, v15, 1.0
	s_andn2_saveexec_b64 s[4:5], s[4:5]
	v_pk_mul_f32 v[60:61], v[14:15], s[88:89] op_sel_hi:[0,1]
	v_add_f32_e32 v61, 1.0, v61
	v_fma_f32 v60, v60, v61, 1.0
	v_mul_f32_e64 v60, v60, -v14
	s_or_b64 exec, exec, s[4:5]
	v_add_f32_e32 v14, v11, v63
	v_mul_f32_e32 v14, 0xbfb8aa3b, v14
	v_exp_f32_e32 v14, v14
	v_max_f32_e32 v60, v60, v60
	v_max_f32_e32 v60, 0, v60
	v_sqrt_f32_e32 v60, v60
	v_add_f32_e32 v14, 1.0, v14
	v_rcp_f32_e32 v14, v14
	s_waitcnt lgkmcnt(0)
	v_lshlrev_b32_e32 v13, 16, v13
	v_add_u32_e32 v139, 12, v72
	v_mul_f32_e32 v14, v14, v60
	v_mul_f32_e32 v13, v14, v13
	v_add_f32_e32 v14, v4, v56
	v_mul_f32_e32 v14, 0xbfb8aa3b, v14
	v_exp_f32_e32 v14, v14
	ds_write2st64_b32 v139, v15, v13 offset0:136 offset1:169
	ds_read_u16 v13, v113 offset:32
	v_add_f32_e32 v14, 1.0, v14
	v_rcp_f32_e64 v14, -v14
	s_nop 0
	v_mul_f32_e32 v14, v97, v14
	v_mul_f32_e32 v15, 0x3fb8aa3b, v14
	v_exp_f32_e32 v15, v15
	v_add_f32_e32 v14, v14, v14
	v_cmp_nlt_f32_e64 s[52:53], s29, v14
	s_and_saveexec_b64 s[4:5], s[52:53]
	s_xor_b64 s[4:5], exec, s[4:5]
	v_fma_f32 v56, -v15, v15, 1.0
	s_andn2_saveexec_b64 s[4:5], s[4:5]
	v_pk_mul_f32 v[60:61], v[14:15], s[88:89] op_sel_hi:[0,1]
	v_add_f32_e32 v56, 1.0, v61
	v_fma_f32 v56, v60, v56, 1.0
	v_mul_f32_e64 v56, v56, -v14
	s_or_b64 exec, exec, s[4:5]
	v_add_f32_e32 v14, v16, v52
	v_mul_f32_e32 v14, 0xbfb8aa3b, v14
	v_exp_f32_e32 v14, v14
	v_max_f32_e32 v52, v56, v56
	v_max_f32_e32 v52, 0, v52
	v_sqrt_f32_e32 v52, v52
	v_add_f32_e32 v14, 1.0, v14
	v_rcp_f32_e32 v14, v14
	s_waitcnt lgkmcnt(0)
	v_lshlrev_b32_e32 v13, 16, v13
	v_add_u32_e32 v141, 64, v72
	v_mul_f32_e32 v14, v14, v52
	v_mul_f32_e32 v13, v14, v13
	v_add_f32_e32 v14, v5, v57
	v_mul_f32_e32 v14, 0xbfb8aa3b, v14
	v_exp_f32_e32 v14, v14
	ds_write2st64_b32 v141, v15, v13 offset0:136 offset1:169
	ds_read_u16 v13, v113 offset:34
	v_add_f32_e32 v14, 1.0, v14
	v_rcp_f32_e64 v14, -v14
	s_nop 0
	v_mul_f32_e32 v14, v98, v14
	v_mul_f32_e32 v15, 0x3fb8aa3b, v14
	v_exp_f32_e32 v15, v15
	v_add_f32_e32 v14, v14, v14
	v_cmp_nlt_f32_e64 s[52:53], s29, v14
	s_and_saveexec_b64 s[4:5], s[52:53]
	s_xor_b64 s[4:5], exec, s[4:5]
	v_fma_f32 v52, -v15, v15, 1.0
	s_andn2_saveexec_b64 s[4:5], s[4:5]
	v_pk_mul_f32 v[56:57], v[14:15], s[88:89] op_sel_hi:[0,1]
	v_add_f32_e32 v52, 1.0, v57
	v_fma_f32 v52, v56, v52, 1.0
	v_mul_f32_e64 v52, v52, -v14
	s_or_b64 exec, exec, s[4:5]
	v_add_f32_e32 v14, v17, v53
	v_mul_f32_e32 v14, 0xbfb8aa3b, v14
	v_exp_f32_e32 v14, v14
	v_max_f32_e32 v52, v52, v52
	v_max_f32_e32 v52, 0, v52
	v_sqrt_f32_e32 v52, v52
	v_add_f32_e32 v14, 1.0, v14
	v_rcp_f32_e32 v14, v14
	s_waitcnt lgkmcnt(0)
	v_lshlrev_b32_e32 v13, 16, v13
	v_add_u32_e32 v142, 0x44, v72
	v_mul_f32_e32 v14, v14, v52
	v_mul_f32_e32 v13, v14, v13
	v_add_f32_e32 v14, v6, v58
	v_mul_f32_e32 v14, 0xbfb8aa3b, v14
	v_exp_f32_e32 v14, v14
	ds_write2st64_b32 v142, v15, v13 offset0:136 offset1:169
	ds_read_u16 v13, v113 offset:36
	v_add_f32_e32 v14, 1.0, v14
	v_rcp_f32_e64 v14, -v14
	s_nop 0
	v_mul_f32_e32 v14, v99, v14
	v_mul_f32_e32 v15, 0x3fb8aa3b, v14
	v_exp_f32_e32 v15, v15
	v_add_f32_e32 v14, v14, v14
	v_cmp_nlt_f32_e64 s[52:53], s29, v14
	s_and_saveexec_b64 s[4:5], s[52:53]
	s_xor_b64 s[4:5], exec, s[4:5]
	v_fma_f32 v52, -v15, v15, 1.0
	s_andn2_saveexec_b64 s[4:5], s[4:5]
	v_pk_mul_f32 v[52:53], v[14:15], s[88:89] op_sel_hi:[0,1]
	v_add_f32_e32 v53, 1.0, v53
	v_fma_f32 v52, v52, v53, 1.0
	v_mul_f32_e64 v52, v52, -v14
	s_or_b64 exec, exec, s[4:5]
	v_add_f32_e32 v14, v18, v54
	v_mul_f32_e32 v14, 0xbfb8aa3b, v14
	v_exp_f32_e32 v14, v14
	v_max_f32_e32 v52, v52, v52
	v_max_f32_e32 v52, 0, v52
	v_sqrt_f32_e32 v52, v52
	v_add_f32_e32 v14, 1.0, v14
	v_rcp_f32_e32 v14, v14
	s_waitcnt lgkmcnt(0)
	v_lshlrev_b32_e32 v13, 16, v13
	v_add_u32_e32 v144, 0x48, v72
	v_mul_f32_e32 v14, v14, v52
	v_mul_f32_e32 v13, v14, v13
	v_add_f32_e32 v14, v7, v59
	v_mul_f32_e32 v14, 0xbfb8aa3b, v14
	v_exp_f32_e32 v14, v14
	ds_write2st64_b32 v144, v15, v13 offset0:136 offset1:169
	ds_read_u16 v13, v113 offset:38
	v_add_f32_e32 v14, 1.0, v14
	v_rcp_f32_e64 v14, -v14
	s_nop 0
	v_mul_f32_e32 v14, v105, v14
	v_mul_f32_e32 v15, 0x3fb8aa3b, v14
	v_exp_f32_e32 v15, v15
	v_add_f32_e32 v14, v14, v14
	v_cmp_nlt_f32_e64 s[52:53], s29, v14
	s_and_saveexec_b64 s[4:5], s[52:53]
	s_xor_b64 s[4:5], exec, s[4:5]
	v_fma_f32 v52, -v15, v15, 1.0
	s_andn2_saveexec_b64 s[4:5], s[4:5]
	v_pk_mul_f32 v[52:53], v[14:15], s[88:89] op_sel_hi:[0,1]
	v_add_f32_e32 v53, 1.0, v53
	v_fma_f32 v52, v52, v53, 1.0
	v_mul_f32_e64 v52, v52, -v14
	s_or_b64 exec, exec, s[4:5]
	v_add_f32_e32 v14, v19, v55
	v_mul_f32_e32 v14, 0xbfb8aa3b, v14
	v_exp_f32_e32 v14, v14
	v_max_f32_e32 v52, v52, v52
	v_max_f32_e32 v52, 0, v52
	v_sqrt_f32_e32 v52, v52
	v_add_f32_e32 v14, 1.0, v14
	v_rcp_f32_e32 v14, v14
	s_waitcnt lgkmcnt(0)
	v_lshlrev_b32_e32 v13, 16, v13
	v_add_u32_e32 v145, 0x4c, v72
	v_add_u32_e32 v137, 0x8800, v114
	v_mul_f32_e32 v14, v14, v52
	v_mul_f32_e32 v13, v14, v13
	v_add_u32_e32 v138, 0xa800, v114
	ds_write2st64_b32 v145, v15, v13 offset0:136 offset1:169
	s_waitcnt lgkmcnt(0)
	s_barrier
; __device__ __forceinline__ float bf2f(bf16_t v) { return __uint_as_float(((unsigned)v) << 16); }
; __device__ __forceinline__ bf16_t f2bf(float f) { return (bf16_t)(cvt_pk_bf16(f, 0.f) & 0xffffu); }
; __device__ __forceinline__ float siluf_(float x) { return x * __builtin_amdgcn_rcpf(1.f + __expf(-x)); }
; __device__ __forceinline__ void rglru_unit(const Params& p, const WS& ws, int j, int u, bool dry = false) {
;     ...
;   auto flush_y = [&]() {
;     if (ypend_t0 >= 0) {
; #pragma unroll
;       for (int i = 0; i < 8; ++i) {
;         const int t = ypend_t0 + 8 * ssg + i;
;         if (t < T_ && !dry) ws.GA[(size_t)(b * T_ + t) * 1024 + 128 * g + 32 * jq + sc] = ypend[i];
;       }
;     }
;   };
;   auto body = [&](int tile, u32x4 (&xin)[4], bf16_t (&gav)[8]) {
;     const int t0 = 64 * tile;
; #pragma unroll
;     for (int i = 0; i < 4; ++i) {
;       const int ci = tid + 256 * i; const int row = ci >> 4, ch = ci & 15;
;       *(u32x4*)(XC + row * 136 + 8 * ch) = xin[i];
;     }
;     float gcur[8];
; #pragma unroll
;     for (int i = 0; i < 8; ++i) gcur[i] = bf2f(gav[i]);
;     __syncthreads();
;     flush_y();
;     if (tile + 2 < 33) prefetch(tile + 2, xin, gav);
;     ...
;     {
;       float A = 1.f, Hh = 0.f;
; #pragma unroll
;       for (int i = 0; i < 8; ++i) {
;         const float a = AUa[(8 * ssg + i) * 33 + sc], uu = AUu[(8 * ssg + i) * 33 + sc];
;         Hh = a * Hh + uu; A *= a;
;       }
;       SEGA[ssg * 32 + sc] = A; SEGH[ssg * 32 + sc] = Hh;
;     }
;     __syncthreads();
;     float hin = CARRY[sc];
; #pragma unroll
;     for (int s2 = 0; s2 < 7; ++s2)
;       if (s2 < ssg) hin = SEGA[s2 * 32 + sc] * hin + SEGH[s2 * 32 + sc];
;     __syncthreads();
;     {
;       float h = hin;
; #pragma unroll
;       for (int i = 0; i < 8; ++i) {
;         const float a = AUa[(8 * ssg + i) * 33 + sc], uu = AUu[(8 * ssg + i) * 33 + sc];
;         h = a * h + uu;
;         const int t = t0 + 8 * ssg + i;
;         ypend[i] = f2bf(h * siluf_(gcur[i]));
;       }
;       if (ssg == 7) CARRY[sc] = h;
;       ypend_t0 = t0;
	ds_read2_b32 v[14:15], v137 offset1:33
	ds_read2_b32 v[52:53], v138 offset0:64 offset1:97
	v_add_u32_e32 v140, 0xac00, v114
	ds_read2_b32 v[204:205], v137 offset0:66 offset1:99
	ds_read2_b32 v[54:55], v138 offset0:130 offset1:163
	ds_read2_b32 v[206:207], v137 offset0:132 offset1:165
	ds_read2_b32 v[244:245], v138 offset0:196 offset1:229
	ds_read2_b32 v[208:209], v137 offset0:198 offset1:231
	ds_read2_b32 v[246:247], v140 offset0:6 offset1:39
	s_waitcnt lgkmcnt(6)
	v_fma_f32 v13, 0, v14, v52
	v_fmac_f32_e32 v53, v13, v15
	v_mul_f32_e32 v13, v14, v15
	s_waitcnt lgkmcnt(4)
	v_mul_f32_e32 v13, v13, v204
	v_fma_f32 v52, v53, v204, v54
	v_fmac_f32_e32 v55, v52, v205
	v_mul_f32_e32 v13, v13, v205
	s_waitcnt lgkmcnt(2)
	v_mul_f32_e32 v13, v13, v206
	v_fma_f32 v244, v55, v206, v244
	v_fmac_f32_e32 v245, v244, v207
	v_mul_f32_e32 v13, v13, v207
	s_waitcnt lgkmcnt(0)
	v_mul_f32_e32 v13, v13, v208
	v_fma_f32 v245, v245, v208, v246
	v_fmac_f32_e32 v247, v245, v209
	v_mul_f32_e32 v13, v13, v209
	ds_write2st64_b32 v78, v13, v247 offset0:202 offset1:206
	s_waitcnt lgkmcnt(0)
	s_barrier
	ds_read_b32 v13, v115 offset:53760
	v_add_u32_e32 v143, 0x80, v115
	ds_read2st64_b32 v[204:205], v115 offset0:202 offset1:206
	ds_read2st64_b32 v[206:207], v143 offset0:202 offset1:206
	ds_read2st64_b32 v[208:209], v115 offset0:203 offset1:207
	ds_read2st64_b32 v[244:245], v143 offset0:203 offset1:207
	ds_read2st64_b32 v[246:247], v115 offset0:204 offset1:208
	ds_read2st64_b32 v[248:249], v143 offset0:204 offset1:208
	ds_read2st64_b32 v[250:251], v115 offset0:205 offset1:209
	s_waitcnt lgkmcnt(6)
	v_fma_f32 v14, v13, v204, v205
	v_cndmask_b32_e32 v13, v13, v14, vcc
	s_waitcnt lgkmcnt(5)
	v_fma_f32 v14, v13, v206, v207
	v_cndmask_b32_e64 v13, v13, v14, s[38:39]
	s_waitcnt lgkmcnt(4)
	v_fma_f32 v14, v13, v208, v209
	v_cndmask_b32_e64 v13, v13, v14, s[40:41]
	s_waitcnt lgkmcnt(3)
	v_fma_f32 v14, v13, v244, v245
	v_cndmask_b32_e64 v13, v13, v14, s[42:43]
	s_waitcnt lgkmcnt(2)
	v_fma_f32 v14, v13, v246, v247
	v_cndmask_b32_e64 v13, v13, v14, s[44:45]
	s_waitcnt lgkmcnt(1)
	v_fma_f32 v14, v13, v248, v249
	v_cndmask_b32_e64 v13, v13, v14, s[46:47]
	s_waitcnt lgkmcnt(0)
	v_fma_f32 v14, v13, v250, v251
	v_cndmask_b32_e64 v13, v13, v14, s[48:49]
.LBB0_1454:
.LBB0_1455:
.LBB0_1456:
.LBB0_1457:
.LBB0_1458:
.LBB0_1459:
.LBB0_1460:
	s_or_b64 exec, exec, s[4:5]
	s_waitcnt lgkmcnt(0)
	s_barrier
	ds_read2_b32 v[14:15], v137 offset1:33
	ds_read2_b32 v[56:57], v138 offset0:64 offset1:97
	s_waitcnt lgkmcnt(0)
	v_fma_f32 v56, v13, v14, v56
	v_fmac_f32_e32 v57, v56, v15
	ds_read2_b32 v[14:15], v137 offset0:66 offset1:99
	ds_read2_b32 v[54:55], v138 offset0:130 offset1:163
	s_waitcnt lgkmcnt(0)
	v_fma_f32 v54, v57, v14, v54
	v_fmac_f32_e32 v55, v54, v15
	ds_read2_b32 v[14:15], v137 offset0:132 offset1:165
	ds_read2_b32 v[52:53], v138 offset0:196 offset1:229
	s_waitcnt lgkmcnt(0)
	v_fma_f32 v52, v55, v14, v52
	v_fmac_f32_e32 v53, v52, v15
	ds_read2_b32 v[58:59], v137 offset0:198 offset1:231
	ds_read2_b32 v[14:15], v140 offset0:6 offset1:39
	s_waitcnt lgkmcnt(0)
	v_fma_f32 v13, v53, v58, v14
	v_fmac_f32_e32 v15, v13, v59
	s_and_saveexec_b64 s[4:5], s[50:51]
	ds_write_b32 v115, v15 offset:53760
	s_or_b64 exec, exec, s[4:5]
	v_lshlrev_b32_e32 v14, 16, v120
	v_mul_f32_e32 v58, 0xbfb8aa3b, v14
	v_exp_f32_e32 v58, v58
	v_lshlrev_b32_e32 v59, 16, v119
	v_lshlrev_b32_e32 v60, 16, v122
	v_lshlrev_b32_e32 v61, 16, v121
	v_add_f32_e32 v58, 1.0, v58
	v_rcp_f32_e32 v58, v58
	v_lshlrev_b32_e32 v62, 16, v124
	v_lshlrev_b32_e32 v63, 16, v123
	v_lshlrev_b32_e32 v64, 16, v128
	v_mul_f32_e32 v14, v58, v14
	v_mul_f32_e32 v14, v14, v56
	v_cvt_pk_bf16_f32 v58, v14, s0
	v_mul_f32_e32 v14, 0xbfb8aa3b, v59
	v_exp_f32_e32 v14, v14
	v_lshlrev_b32_e32 v65, 16, v127
	s_cmp_gt_u32 s7, 32
	v_add_f32_e32 v14, 1.0, v14
	v_rcp_f32_e32 v14, v14
	s_nop 0
	v_mul_f32_e32 v14, v14, v59
	v_mul_f32_e32 v14, v14, v57
	v_cvt_pk_bf16_f32 v59, v14, s0
	v_mul_f32_e32 v14, 0xbfb8aa3b, v60
	v_exp_f32_e32 v14, v14
	s_nop 0
	v_add_f32_e32 v14, 1.0, v14
	v_rcp_f32_e32 v14, v14
	s_nop 0
	v_mul_f32_e32 v14, v14, v60
	v_mul_f32_e32 v14, v14, v54
	v_cvt_pk_bf16_f32 v56, v14, s0
	v_mul_f32_e32 v14, 0xbfb8aa3b, v61
	v_exp_f32_e32 v14, v14
	s_nop 0
	v_add_f32_e32 v14, 1.0, v14
	v_rcp_f32_e32 v14, v14
	s_nop 0
	v_mul_f32_e32 v14, v14, v61
	v_mul_f32_e32 v14, v14, v55
	v_cvt_pk_bf16_f32 v57, v14, s0
	v_mul_f32_e32 v14, 0xbfb8aa3b, v62
	v_exp_f32_e32 v14, v14
	s_nop 0
	v_add_f32_e32 v14, 1.0, v14
	v_rcp_f32_e32 v14, v14
	s_nop 0
	v_mul_f32_e32 v14, v14, v62
	v_mul_f32_e32 v14, v14, v52
	v_cvt_pk_bf16_f32 v54, v14, s0
	v_mul_f32_e32 v14, 0xbfb8aa3b, v63
	v_exp_f32_e32 v14, v14
	s_nop 0
	v_add_f32_e32 v14, 1.0, v14
	v_rcp_f32_e32 v14, v14
	s_nop 0
	v_mul_f32_e32 v14, v14, v63
	v_mul_f32_e32 v14, v14, v53
	v_cvt_pk_bf16_f32 v55, v14, s0
	v_mul_f32_e32 v14, 0xbfb8aa3b, v64
	v_exp_f32_e32 v14, v14
	s_nop 0
	v_add_f32_e32 v14, 1.0, v14
	v_rcp_f32_e32 v14, v14
	s_nop 0
	v_mul_f32_e32 v14, v14, v64
	v_mul_f32_e32 v13, v14, v13
	v_cvt_pk_bf16_f32 v14, v13, s0
	v_mul_f32_e32 v13, 0xbfb8aa3b, v65
	v_exp_f32_e32 v13, v13
	s_nop 0
	v_add_f32_e32 v13, 1.0, v13
	v_rcp_f32_e32 v13, v13
	s_nop 0
	v_mul_f32_e32 v13, v13, v65
	v_mul_f32_e32 v13, v13, v15
	v_cvt_pk_bf16_f32 v15, v13, s0
	s_cbranch_scc1 .LBB0_1554
	v_add_u32_e32 v60, s6, v83
	v_cmp_gt_i32_e64 s[52:53], s15, v60
	v_add_u32_e32 v52, s6, v69
	s_waitcnt vmcnt(8)
	ds_write_b128 v106, v[36:39]
	ds_write_b128 v107, v[40:43]
	ds_write_b128 v109, v[44:47]
	ds_write_b128 v110, v[48:51]
	s_waitcnt lgkmcnt(0)
	s_barrier
	s_cmpk_gt_i32 s6, 0x7d0
	s_cbranch_scc1 .Lrg_fslow2
	s_mov_b64 s[4:5], 0x1000
	v_ashrrev_i32_e32 v53, 31, v52
	v_lshlrev_b64 v[62:63], 11, v[52:53]
	v_lshl_add_u64 v[62:63], v[74:75], 0, v[62:63]
	global_store_short v[62:63], v58, off
	global_store_short v[62:63], v59, off offset:2048
	v_lshl_add_u64 v[62:63], v[62:63], 0, s[4:5]
	global_store_short v[62:63], v56, off
	global_store_short v[62:63], v57, off offset:2048
	v_lshl_add_u64 v[62:63], v[62:63], 0, s[4:5]
	global_store_short v[62:63], v54, off
	global_store_short v[62:63], v55, off offset:2048
	v_lshl_add_u64 v[62:63], v[62:63], 0, s[4:5]
	global_store_short v[62:63], v14, off
	global_store_short v[62:63], v15, off offset:2048
	s_branch .Lrg_fjoin2

; __device__ __forceinline__ float bf2f(bf16_t v) { return __uint_as_float(((unsigned)v) << 16); }
; __device__ __forceinline__ float sigmoidf_(float x) { return __builtin_amdgcn_rcpf(1.f + __expf(-x)); }
; #define MFMA16(a, b, c) __builtin_amdgcn_mfma_f32_16x16x32_bf16((a), (b), (c), 0, 0, 0)
; __device__ __forceinline__ void rglru_unit(const Params& p, const WS& ws, int j, int u, bool dry = false) {
;     ...
;       for (int ks = 0; ks < 4; ++ks) {
;         const bf16x8 xf = *(const bf16x8*)(XC + (16 * w + lr) * 136 + 32 * ks + 8 * lq);
; #pragma unroll
;         for (int gate = 0; gate < 2; ++gate)
; #pragma unroll
;           for (int mt = 0; mt < 2; ++mt) {
;             const bf16x8 wf = *(const bf16x8*)(WG + (gate * 32 + 16 * mt + lr) * 136 + 32 * ks + 8 * lq);
;             ga_[gate][mt] = MFMA16(wf, xf, ga_[gate][mt]);
;           }
;       }
;       const int tok = 16 * w + lr;
; #pragma unroll
;       for (int mt = 0; mt < 2; ++mt)
; #pragma unroll
;         for (int jj = 0; jj < 4; ++jj) {
;           const int n = 16 * mt + 4 * lq + jj;
;           const float xcv = bf2f(XC[tok * 136 + 32 * jq + n]);
;           const float r = sigmoidf_(ga_[0][mt][jj] + ba[mt][jj]);
;           const float ig = sigmoidf_(ga_[1][mt][jj] + bx[mt][jj]);
;           const float la = -r * sp[mt][jj];
;           const float a = __expf(la);
;           const float x2 = 2.f * la;
;           const float om = x2 > -0.02f ? -x2 * (1.f + 0.5f * x2 * (1.f + x2 * (1.f / 3.f))) : 1.f - a * a;
;           const float mult = __builtin_amdgcn_sqrtf(fmaxf(om, 0.f));
;           AUa[tok * 33 + n] = a;
;           AUu[tok * 33 + n] = mult * ig * xcv;
;         }
.LBB0_1505:
	ds_read_b128 v[52:55], v111
	ds_read_b128 v[56:59], v112 offset:17408
	ds_read_b128 v[60:63], v112 offset:21760
	ds_read_b128 v[64:67], v112 offset:26112
	ds_read_b128 v[120:123], v112 offset:30464
	ds_read_b128 v[212:215], v111 offset:64
	ds_read_b128 v[216:219], v111 offset:128
	ds_read_b128 v[220:223], v111 offset:192
	ds_read_b128 v[224:227], v112 offset:17472
	ds_read_b128 v[228:231], v112 offset:21824
	ds_read_b128 v[232:235], v112 offset:26176
	ds_read_b128 v[244:247], v112 offset:30528
	ds_read_b128 v[248:251], v112 offset:17536
	ds_read_b128 v[252:255], v112 offset:21888
	s_waitcnt lgkmcnt(12)
	v_mfma_f32_16x16x32_bf16 v[56:59], v[56:59], v[52:55], 0
	s_waitcnt lgkmcnt(11)
	v_mfma_f32_16x16x32_bf16 v[60:63], v[60:63], v[52:55], 0
	s_waitcnt lgkmcnt(10)
	v_mfma_f32_16x16x32_bf16 v[64:67], v[64:67], v[52:55], 0
	s_waitcnt lgkmcnt(9)
	v_mfma_f32_16x16x32_bf16 v[52:55], v[120:123], v[52:55], 0
	s_nop 0
	s_nop 0
	s_waitcnt lgkmcnt(5)
	v_mfma_f32_16x16x32_bf16 v[56:59], v[224:227], v[212:215], v[56:59]
	ds_read_b128 v[224:227], v112 offset:26240
	s_nop 0
	s_waitcnt lgkmcnt(5)
	v_mfma_f32_16x16x32_bf16 v[60:63], v[228:231], v[212:215], v[60:63]
	ds_read_b128 v[228:231], v112 offset:30592
	s_nop 0
	s_waitcnt lgkmcnt(5)
	v_mfma_f32_16x16x32_bf16 v[64:67], v[232:235], v[212:215], v[64:67]
	ds_read_b128 v[232:235], v112 offset:17600
	s_nop 0
	s_waitcnt lgkmcnt(5)
	v_mfma_f32_16x16x32_bf16 v[52:55], v[244:247], v[212:215], v[52:55]
	ds_read_b128 v[244:247], v112 offset:21952
	s_nop 0
	s_nop 0
	s_waitcnt lgkmcnt(5)
	v_mfma_f32_16x16x32_bf16 v[56:59], v[248:251], v[216:219], v[56:59]
	ds_read_b128 v[248:251], v112 offset:26304
	s_nop 0
	s_waitcnt lgkmcnt(5)
	v_mfma_f32_16x16x32_bf16 v[60:63], v[252:255], v[216:219], v[60:63]
	ds_read_b128 v[252:255], v112 offset:30656
	s_nop 0
	s_waitcnt lgkmcnt(5)
	v_mfma_f32_16x16x32_bf16 v[154:157], v[224:227], v[216:219], v[64:67]
	s_nop 2
	s_nop 0
	s_waitcnt lgkmcnt(4)
	v_mfma_f32_16x16x32_bf16 v[52:55], v[228:231], v[216:219], v[52:55]
	s_nop 0
	s_nop 0
	ds_read_u16 v15, v113
	s_waitcnt lgkmcnt(4)
	v_mfma_f32_16x16x32_bf16 v[64:67], v[232:235], v[220:223], v[56:59]
	s_nop 2
	s_nop 0
	s_waitcnt lgkmcnt(3)
	v_mfma_f32_16x16x32_bf16 v[56:59], v[244:247], v[220:223], v[60:63]
	s_nop 2
	s_nop 0
	v_add_f32_e32 v14, v0, v64
	v_mul_f32_e32 v14, 0xbfb8aa3b, v14
	v_exp_f32_e32 v14, v14
	s_waitcnt lgkmcnt(2)
	v_mfma_f32_16x16x32_bf16 v[60:63], v[248:251], v[220:223], v[154:157]
	s_nop 2
	s_nop 0
	v_add_f32_e32 v14, 1.0, v14
	v_rcp_f32_e64 v14, -v14
	s_waitcnt lgkmcnt(0)
	v_mfma_f32_16x16x32_bf16 v[52:55], v[252:255], v[220:223], v[52:55]
	v_mul_f32_e32 v14, v89, v14
	v_mul_f32_e32 v64, 0x3fb8aa3b, v14
	v_exp_f32_e32 v64, v64
	v_add_f32_e32 v14, v14, v14
	v_cmp_nlt_f32_e64 s[52:53], s29, v14
	s_and_saveexec_b64 s[4:5], s[52:53]
	s_xor_b64 s[4:5], exec, s[4:5]
	v_fma_f32 v119, -v64, v64, 1.0
	s_andn2_saveexec_b64 s[4:5], s[4:5]
	v_pk_mul_f32 v[120:121], v[14:15], s[88:89] op_sel_hi:[0,1]
	v_add_f32_e32 v119, 1.0, v121
	v_fma_f32 v119, v120, v119, 1.0
	v_mul_f32_e64 v119, v119, -v14
	s_or_b64 exec, exec, s[4:5]
	v_add_f32_e32 v14, v8, v60
	v_add_f32_e32 v65, v1, v65
	v_mul_f32_e32 v14, 0xbfb8aa3b, v14
	v_mul_f32_e32 v65, 0xbfb8aa3b, v65
	v_exp_f32_e32 v14, v14
	v_exp_f32_e32 v65, v65
	v_max_f32_e32 v60, v119, v119
	v_max_f32_e32 v60, 0, v60
	v_add_f32_e32 v14, 1.0, v14
	v_add_f32_e32 v65, 1.0, v65
	v_rcp_f32_e32 v14, v14
	v_sqrt_f32_e32 v60, v60
	v_rcp_f32_e64 v65, -v65
	v_lshlrev_b32_e32 v15, 16, v15
	v_mul_f32_e32 v14, v14, v60
	v_mul_f32_e32 v65, v93, v65
	v_mul_f32_e32 v14, v14, v15
	ds_read_u16 v60, v113 offset:2
	v_mul_f32_e32 v15, 0x3fb8aa3b, v65
	v_exp_f32_e32 v15, v15
	ds_write2st64_b32 v72, v64, v14 offset0:136 offset1:169
	v_add_f32_e32 v14, v65, v65
	v_cmp_nlt_f32_e64 s[52:53], s29, v14
	s_and_saveexec_b64 s[4:5], s[52:53]
	s_xor_b64 s[4:5], exec, s[4:5]
	v_fma_f32 v64, -v15, v15, 1.0
	s_andn2_saveexec_b64 s[4:5], s[4:5]
	v_pk_mul_f32 v[64:65], v[14:15], s[88:89] op_sel_hi:[0,1]
	v_add_f32_e32 v65, 1.0, v65
	v_fma_f32 v64, v64, v65, 1.0
	v_mul_f32_e64 v64, v64, -v14
	s_or_b64 exec, exec, s[4:5]
	v_add_f32_e32 v14, v9, v61
	v_max_f32_e32 v61, v64, v64
	v_add_f32_e32 v64, v2, v66
	v_mul_f32_e32 v14, 0xbfb8aa3b, v14
	v_mul_f32_e32 v64, 0xbfb8aa3b, v64
	v_exp_f32_e32 v14, v14
	v_exp_f32_e32 v64, v64
	v_max_f32_e32 v61, 0, v61
	v_sqrt_f32_e32 v61, v61
	v_add_f32_e32 v14, 1.0, v14
	v_add_f32_e32 v64, 1.0, v64
	v_rcp_f32_e32 v14, v14
	v_rcp_f32_e64 v64, -v64
	s_waitcnt lgkmcnt(1)
	v_lshlrev_b32_e32 v60, 16, v60
	v_mul_f32_e32 v14, v14, v61
	v_mul_f32_e32 v64, v95, v64
	v_mul_f32_e32 v14, v14, v60
	ds_read_u16 v61, v113 offset:4
	v_mul_f32_e32 v60, 0x3fb8aa3b, v64
	v_exp_f32_e32 v60, v60
	ds_write2st64_b32 v135, v15, v14 offset0:136 offset1:169
	v_add_f32_e32 v14, v64, v64
	v_cmp_nlt_f32_e64 s[52:53], s29, v14
	s_and_saveexec_b64 s[4:5], s[52:53]
	s_xor_b64 s[4:5], exec, s[4:5]
	v_fma_f32 v15, -v60, v60, 1.0
	s_andn2_saveexec_b64 s[4:5], s[4:5]
	v_pk_mul_f32 v[64:65], v[14:15], s[88:89] op_sel_hi:[0,1]
	v_add_f32_e32 v15, 1.0, v65
	v_fma_f32 v15, v64, v15, 1.0
	v_mul_f32_e64 v15, v15, -v14
	s_or_b64 exec, exec, s[4:5]
	v_add_f32_e32 v14, v10, v62
	v_add_f32_e32 v62, v3, v67
	v_mul_f32_e32 v14, 0xbfb8aa3b, v14
	v_mul_f32_e32 v62, 0xbfb8aa3b, v62
	v_exp_f32_e32 v14, v14
	v_exp_f32_e32 v62, v62
	v_max_f32_e32 v15, v15, v15
	v_max_f32_e32 v15, 0, v15
	v_add_f32_e32 v14, 1.0, v14
	v_add_f32_e32 v62, 1.0, v62
	v_rcp_f32_e32 v14, v14
	v_sqrt_f32_e32 v15, v15
	v_rcp_f32_e64 v62, -v62
	s_waitcnt lgkmcnt(1)
; __device__ __forceinline__ float bf2f(bf16_t v) { return __uint_as_float(((unsigned)v) << 16); }
; __device__ __forceinline__ float sigmoidf_(float x) { return __builtin_amdgcn_rcpf(1.f + __expf(-x)); }
; __device__ __forceinline__ void rglru_unit(const Params& p, const WS& ws, int j, int u, bool dry = false) {
;     ...
; #pragma unroll
;       for (int mt = 0; mt < 2; ++mt)
; #pragma unroll
;         for (int jj = 0; jj < 4; ++jj) {
;           const int n = 16 * mt + 4 * lq + jj;
;           const float xcv = bf2f(XC[tok * 136 + 32 * jq + n]);
;           const float r = sigmoidf_(ga_[0][mt][jj] + ba[mt][jj]);
;           const float ig = sigmoidf_(ga_[1][mt][jj] + bx[mt][jj]);
;           const float la = -r * sp[mt][jj];
;           const float a = __expf(la);
;           const float x2 = 2.f * la;
;           const float om = x2 > -0.02f ? -x2 * (1.f + 0.5f * x2 * (1.f + x2 * (1.f / 3.f))) : 1.f - a * a;
;           const float mult = __builtin_amdgcn_sqrtf(fmaxf(om, 0.f));
;           AUa[tok * 33 + n] = a;
;           AUu[tok * 33 + n] = mult * ig * xcv;
;         }
;     }
;     __syncthreads();
	v_lshlrev_b32_e32 v61, 16, v61
	v_mul_f32_e32 v14, v14, v15
	v_mul_f32_e32 v62, v96, v62
	v_mul_f32_e32 v14, v14, v61
	ds_read_u16 v61, v113 offset:6
	v_mul_f32_e32 v15, 0x3fb8aa3b, v62
	v_exp_f32_e32 v15, v15
	ds_write2st64_b32 v136, v60, v14 offset0:136 offset1:169
	v_add_f32_e32 v14, v62, v62
	v_cmp_nlt_f32_e64 s[52:53], s29, v14
	s_and_saveexec_b64 s[4:5], s[52:53]
	s_xor_b64 s[4:5], exec, s[4:5]
	v_fma_f32 v60, -v15, v15, 1.0
	s_andn2_saveexec_b64 s[4:5], s[4:5]
	v_pk_mul_f32 v[64:65], v[14:15], s[88:89] op_sel_hi:[0,1]
	v_add_f32_e32 v60, 1.0, v65
	v_fma_f32 v60, v64, v60, 1.0
	v_mul_f32_e64 v60, v60, -v14
	s_or_b64 exec, exec, s[4:5]
	v_add_f32_e32 v14, v11, v63
	v_mul_f32_e32 v14, 0xbfb8aa3b, v14
	v_add_f32_e32 v56, v4, v56
	v_exp_f32_e32 v14, v14
	v_mul_f32_e32 v56, 0xbfb8aa3b, v56
	v_exp_f32_e32 v56, v56
	v_max_f32_e32 v60, v60, v60
	v_add_f32_e32 v14, 1.0, v14
	v_max_f32_e32 v60, 0, v60
	v_rcp_f32_e32 v14, v14
	v_sqrt_f32_e32 v60, v60
	v_add_f32_e32 v56, 1.0, v56
	v_rcp_f32_e64 v56, -v56
	s_waitcnt lgkmcnt(1)
	v_lshlrev_b32_e32 v61, 16, v61
	v_mul_f32_e32 v14, v14, v60
	v_mul_f32_e32 v14, v14, v61
	v_mul_f32_e32 v61, v97, v56
	ds_read_u16 v60, v113 offset:32
	v_mul_f32_e32 v56, 0x3fb8aa3b, v61
	v_exp_f32_e32 v56, v56
	ds_write2st64_b32 v139, v15, v14 offset0:136 offset1:169
	v_add_f32_e32 v14, v61, v61
	v_cmp_nlt_f32_e64 s[52:53], s29, v14
	s_and_saveexec_b64 s[4:5], s[52:53]
	s_xor_b64 s[4:5], exec, s[4:5]
	v_fma_f32 v15, -v56, v56, 1.0
	s_andn2_saveexec_b64 s[4:5], s[4:5]
	v_pk_mul_f32 v[62:63], v[14:15], s[88:89] op_sel_hi:[0,1]
	v_add_f32_e32 v15, 1.0, v63
	v_fma_f32 v15, v62, v15, 1.0
	v_mul_f32_e64 v15, v15, -v14
	s_or_b64 exec, exec, s[4:5]
	v_add_f32_e32 v14, v16, v52
	v_mul_f32_e32 v14, 0xbfb8aa3b, v14
	v_add_f32_e32 v52, v5, v57
	v_exp_f32_e32 v14, v14
	v_mul_f32_e32 v52, 0xbfb8aa3b, v52
	v_exp_f32_e32 v52, v52
	v_max_f32_e32 v15, v15, v15
	v_add_f32_e32 v14, 1.0, v14
	v_max_f32_e32 v15, 0, v15
	v_rcp_f32_e32 v14, v14
	v_sqrt_f32_e32 v15, v15
	v_add_f32_e32 v52, 1.0, v52
	s_waitcnt lgkmcnt(1)
	v_lshlrev_b32_e32 v57, 16, v60
	v_rcp_f32_e64 v60, -v52
	v_mul_f32_e32 v14, v14, v15
	v_mul_f32_e32 v14, v14, v57
	ds_read_u16 v52, v113 offset:34
	v_mul_f32_e32 v57, v98, v60
	v_mul_f32_e32 v15, 0x3fb8aa3b, v57
	v_exp_f32_e32 v15, v15
	ds_write2st64_b32 v141, v56, v14 offset0:136 offset1:169
	v_add_f32_e32 v14, v57, v57
	v_cmp_nlt_f32_e64 s[52:53], s29, v14
	s_and_saveexec_b64 s[4:5], s[52:53]
	s_xor_b64 s[4:5], exec, s[4:5]
	v_fma_f32 v56, -v15, v15, 1.0
	s_andn2_saveexec_b64 s[4:5], s[4:5]
	v_pk_mul_f32 v[56:57], v[14:15], s[88:89] op_sel_hi:[0,1]
	v_add_f32_e32 v57, 1.0, v57
	v_fma_f32 v56, v56, v57, 1.0
	v_mul_f32_e64 v56, v56, -v14
	s_or_b64 exec, exec, s[4:5]
	v_add_f32_e32 v14, v17, v53
	v_max_f32_e32 v53, v56, v56
	v_add_f32_e32 v56, v6, v58
	v_mul_f32_e32 v14, 0xbfb8aa3b, v14
	v_mul_f32_e32 v56, 0xbfb8aa3b, v56
	v_exp_f32_e32 v14, v14
	v_exp_f32_e32 v56, v56
	v_max_f32_e32 v53, 0, v53
	v_sqrt_f32_e32 v53, v53
	v_add_f32_e32 v14, 1.0, v14
	v_add_f32_e32 v56, 1.0, v56
	v_rcp_f32_e32 v14, v14
	v_rcp_f32_e64 v56, -v56
	s_waitcnt lgkmcnt(1)
	v_lshlrev_b32_e32 v52, 16, v52
	v_mul_f32_e32 v14, v14, v53
	v_mul_f32_e32 v56, v99, v56
	v_mul_f32_e32 v14, v14, v52
	ds_read_u16 v53, v113 offset:36
	v_mul_f32_e32 v52, 0x3fb8aa3b, v56
	v_exp_f32_e32 v52, v52
	ds_write2st64_b32 v142, v15, v14 offset0:136 offset1:169
	v_add_f32_e32 v14, v56, v56
	v_cmp_nlt_f32_e64 s[52:53], s29, v14
	s_and_saveexec_b64 s[4:5], s[52:53]
	s_xor_b64 s[4:5], exec, s[4:5]
	v_fma_f32 v15, -v52, v52, 1.0
	s_andn2_saveexec_b64 s[4:5], s[4:5]
	v_pk_mul_f32 v[56:57], v[14:15], s[88:89] op_sel_hi:[0,1]
	v_add_f32_e32 v15, 1.0, v57
	v_fma_f32 v15, v56, v15, 1.0
	v_mul_f32_e64 v15, v15, -v14
	s_or_b64 exec, exec, s[4:5]
	v_add_f32_e32 v14, v18, v54
	v_add_f32_e32 v54, v7, v59
	v_mul_f32_e32 v14, 0xbfb8aa3b, v14
	v_mul_f32_e32 v54, 0xbfb8aa3b, v54
	v_exp_f32_e32 v14, v14
	v_exp_f32_e32 v54, v54
	v_max_f32_e32 v15, v15, v15
	v_max_f32_e32 v15, 0, v15
	v_add_f32_e32 v14, 1.0, v14
	v_add_f32_e32 v54, 1.0, v54
	v_rcp_f32_e32 v14, v14
	v_sqrt_f32_e32 v15, v15
	v_rcp_f32_e64 v54, -v54
	s_waitcnt lgkmcnt(1)
	v_lshlrev_b32_e32 v53, 16, v53
	v_mul_f32_e32 v14, v14, v15
	v_mul_f32_e32 v54, v105, v54
	v_mul_f32_e32 v14, v14, v53
	ds_read_u16 v53, v113 offset:38
	v_mul_f32_e32 v15, 0x3fb8aa3b, v54
	v_exp_f32_e32 v15, v15
	ds_write2st64_b32 v144, v52, v14 offset0:136 offset1:169
	v_add_f32_e32 v14, v54, v54
	v_cmp_nlt_f32_e64 s[52:53], s29, v14
	s_and_saveexec_b64 s[4:5], s[52:53]
	s_xor_b64 s[4:5], exec, s[4:5]
	v_fma_f32 v52, -v15, v15, 1.0
	s_andn2_saveexec_b64 s[4:5], s[4:5]
	v_pk_mul_f32 v[56:57], v[14:15], s[88:89] op_sel_hi:[0,1]
	v_add_f32_e32 v52, 1.0, v57
	v_fma_f32 v52, v56, v52, 1.0
	v_mul_f32_e64 v52, v52, -v14
	s_or_b64 exec, exec, s[4:5]
	s_waitcnt lgkmcnt(1)
	v_lshlrev_b32_e32 v14, 16, v53
	v_add_f32_e32 v53, v19, v55
	v_mul_f32_e32 v53, 0xbfb8aa3b, v53
	v_exp_f32_e32 v53, v53
	v_max_f32_e32 v52, v52, v52
	v_max_f32_e32 v52, 0, v52
	v_sqrt_f32_e32 v52, v52
	v_add_f32_e32 v53, 1.0, v53
	v_rcp_f32_e32 v53, v53
	s_nop 0
	v_mul_f32_e32 v52, v53, v52
	v_mul_f32_e32 v14, v52, v14
	ds_write2st64_b32 v145, v15, v14 offset0:136 offset1:169
	s_waitcnt lgkmcnt(0)
	s_barrier
; __device__ __forceinline__ bf16_t f2bf(float f) { return (bf16_t)(cvt_pk_bf16(f, 0.f) & 0xffffu); }
; __device__ __forceinline__ float siluf_(float x) { return x * __builtin_amdgcn_rcpf(1.f + __expf(-x)); }
; __device__ __forceinline__ void rglru_unit(const Params& p, const WS& ws, int j, int u, bool dry = false) {
;     ...
;     {
;       float A = 1.f, Hh = 0.f;
; #pragma unroll
;       for (int i = 0; i < 8; ++i) {
;         const float a = AUa[(8 * ssg + i) * 33 + sc], uu = AUu[(8 * ssg + i) * 33 + sc];
;         Hh = a * Hh + uu; A *= a;
;       }
;       SEGA[ssg * 32 + sc] = A; SEGH[ssg * 32 + sc] = Hh;
;     }
;     __syncthreads();
;     float hin = CARRY[sc];
; #pragma unroll
;     for (int s2 = 0; s2 < 7; ++s2)
;       if (s2 < ssg) hin = SEGA[s2 * 32 + sc] * hin + SEGH[s2 * 32 + sc];
;     __syncthreads();
;     {
;       float h = hin;
; #pragma unroll
;       for (int i = 0; i < 8; ++i) {
;         const float a = AUa[(8 * ssg + i) * 33 + sc], uu = AUu[(8 * ssg + i) * 33 + sc];
;         h = a * h + uu;
;         const int t = t0 + 8 * ssg + i;
;         ypend[i] = f2bf(h * siluf_(gcur[i]));
;       }
;       if (ssg == 7) CARRY[sc] = h;
;       ypend_t0 = t0;
	ds_read2_b32 v[14:15], v137 offset1:33
	ds_read2_b32 v[52:53], v138 offset0:64 offset1:97
	s_nop 0
	ds_read2_b32 v[204:205], v137 offset0:66 offset1:99
	ds_read2_b32 v[54:55], v138 offset0:130 offset1:163
	ds_read2_b32 v[206:207], v137 offset0:132 offset1:165
	ds_read2_b32 v[244:245], v138 offset0:196 offset1:229
	ds_read2_b32 v[208:209], v137 offset0:198 offset1:231
	ds_read2_b32 v[246:247], v140 offset0:6 offset1:39
	s_waitcnt lgkmcnt(6)
	v_fma_f32 v52, 0, v14, v52
	v_fmac_f32_e32 v53, v52, v15
	v_mul_f32_e32 v52, v14, v15
	s_waitcnt lgkmcnt(4)
	v_fma_f32 v53, v53, v204, v54
	v_mul_f32_e32 v14, v52, v204
	v_fmac_f32_e32 v55, v53, v205
	v_mul_f32_e32 v54, v14, v205
	s_waitcnt lgkmcnt(2)
	v_fma_f32 v244, v55, v206, v244
	v_mul_f32_e32 v14, v54, v206
	v_fmac_f32_e32 v245, v244, v207
	v_mul_f32_e32 v52, v14, v207
	s_waitcnt lgkmcnt(0)
	v_fma_f32 v245, v245, v208, v246
	v_mul_f32_e32 v14, v52, v208
	v_fmac_f32_e32 v247, v245, v209
	v_mul_f32_e32 v14, v14, v209
	ds_write2st64_b32 v78, v14, v247 offset0:202 offset1:206
	s_waitcnt lgkmcnt(0)
	s_barrier
	ds_read_b32 v14, v115 offset:53760
	ds_read2st64_b32 v[204:205], v115 offset0:202 offset1:206
	ds_read2st64_b32 v[206:207], v143 offset0:202 offset1:206
	ds_read2st64_b32 v[208:209], v115 offset0:203 offset1:207
	ds_read2st64_b32 v[244:245], v143 offset0:203 offset1:207
	ds_read2st64_b32 v[246:247], v115 offset0:204 offset1:208
	ds_read2st64_b32 v[248:249], v143 offset0:204 offset1:208
	ds_read2st64_b32 v[250:251], v115 offset0:205 offset1:209
	s_waitcnt lgkmcnt(6)
	v_fma_f32 v52, v14, v204, v205
	v_cndmask_b32_e32 v14, v14, v52, vcc
	s_waitcnt lgkmcnt(5)
	v_fma_f32 v52, v14, v206, v207
	v_cndmask_b32_e64 v14, v14, v52, s[38:39]
	s_waitcnt lgkmcnt(4)
	v_fma_f32 v52, v14, v208, v209
	v_cndmask_b32_e64 v14, v14, v52, s[40:41]
	s_waitcnt lgkmcnt(3)
	v_fma_f32 v52, v14, v244, v245
	v_cndmask_b32_e64 v14, v14, v52, s[42:43]
	s_waitcnt lgkmcnt(2)
	v_fma_f32 v52, v14, v246, v247
	v_cndmask_b32_e64 v14, v14, v52, s[44:45]
	s_waitcnt lgkmcnt(1)
	v_fma_f32 v52, v14, v248, v249
	v_cndmask_b32_e64 v14, v14, v52, s[46:47]
	s_waitcnt lgkmcnt(0)
	v_fma_f32 v52, v14, v250, v251
	v_cndmask_b32_e64 v14, v14, v52, s[48:49]
.LBB0_1539:
.LBB0_1540:
.LBB0_1541:
.LBB0_1542:
.LBB0_1543:
.LBB0_1544:
.LBB0_1545:
	s_or_b64 exec, exec, s[4:5]
	s_waitcnt lgkmcnt(0)
	s_barrier
	ds_read2_b32 v[52:53], v137 offset1:33
	ds_read2_b32 v[56:57], v138 offset0:64 offset1:97
	s_waitcnt lgkmcnt(0)
	v_fma_f32 v56, v14, v52, v56
	ds_read2_b32 v[14:15], v137 offset0:66 offset1:99
	ds_read2_b32 v[54:55], v138 offset0:130 offset1:163
	v_fmac_f32_e32 v57, v56, v53
	s_waitcnt lgkmcnt(0)
	v_fma_f32 v54, v57, v14, v54
	v_fmac_f32_e32 v55, v54, v15
	ds_read2_b32 v[14:15], v137 offset0:132 offset1:165
	ds_read2_b32 v[52:53], v138 offset0:196 offset1:229
	s_waitcnt lgkmcnt(0)
	v_fma_f32 v52, v55, v14, v52
	v_fmac_f32_e32 v53, v52, v15
	ds_read2_b32 v[58:59], v137 offset0:198 offset1:231
	ds_read2_b32 v[14:15], v140 offset0:6 offset1:39
	s_waitcnt lgkmcnt(0)
	v_fma_f32 v14, v53, v58, v14
	v_fmac_f32_e32 v15, v14, v59
	s_and_saveexec_b64 s[4:5], s[50:51]
	ds_write_b32 v115, v15 offset:53760
	s_or_b64 exec, exec, s[4:5]
	v_lshlrev_b32_e32 v58, 16, v86
	v_mul_f32_e32 v66, 0xbfb8aa3b, v58
	v_exp_f32_e32 v66, v66
	v_lshlrev_b32_e32 v59, 16, v85
	v_lshlrev_b32_e32 v60, 16, v88
	v_lshlrev_b32_e32 v61, 16, v87
	v_add_f32_e32 v66, 1.0, v66
	v_rcp_f32_e32 v66, v66
	v_lshlrev_b32_e32 v62, 16, v91
	v_lshlrev_b32_e32 v63, 16, v90
	v_lshlrev_b32_e32 v64, 16, v92
	v_mul_f32_e32 v58, v66, v58
	v_mul_f32_e32 v56, v58, v56
	v_cvt_pk_bf16_f32 v58, v56, s0
	v_mul_f32_e32 v56, 0xbfb8aa3b, v59
	v_exp_f32_e32 v56, v56
	v_lshlrev_b32_e32 v65, 16, v94
	s_add_i32 s4, s6, 64
	v_add_f32_e32 v56, 1.0, v56
	v_rcp_f32_e32 v56, v56
	s_nop 0
	v_mul_f32_e32 v56, v56, v59
	v_mul_f32_e32 v56, v56, v57
	v_cvt_pk_bf16_f32 v59, v56, s0
	v_mul_f32_e32 v56, 0xbfb8aa3b, v60
	v_exp_f32_e32 v56, v56
	s_nop 0
	v_add_f32_e32 v56, 1.0, v56
	v_rcp_f32_e32 v56, v56
	s_nop 0
	v_mul_f32_e32 v56, v56, v60
	v_mul_f32_e32 v54, v56, v54
	v_cvt_pk_bf16_f32 v56, v54, s0
	v_mul_f32_e32 v54, 0xbfb8aa3b, v61
	v_exp_f32_e32 v54, v54
	s_nop 0
	v_add_f32_e32 v54, 1.0, v54
	v_rcp_f32_e32 v54, v54
	s_nop 0
	v_mul_f32_e32 v54, v54, v61
	v_mul_f32_e32 v54, v54, v55
	v_cvt_pk_bf16_f32 v57, v54, s0
	v_mul_f32_e32 v54, 0xbfb8aa3b, v62
	v_exp_f32_e32 v54, v54
	s_nop 0
	v_add_f32_e32 v54, 1.0, v54
	v_rcp_f32_e32 v54, v54
	s_nop 0
	v_mul_f32_e32 v54, v54, v62
	v_mul_f32_e32 v52, v54, v52
	v_cvt_pk_bf16_f32 v54, v52, s0
	v_mul_f32_e32 v52, 0xbfb8aa3b, v63
	v_exp_f32_e32 v52, v52
	s_nop 0
	v_add_f32_e32 v52, 1.0, v52
	v_rcp_f32_e32 v52, v52
	s_nop 0
	v_mul_f32_e32 v52, v52, v63
	v_mul_f32_e32 v52, v52, v53
	v_cvt_pk_bf16_f32 v55, v52, s0
	v_mul_f32_e32 v52, 0xbfb8aa3b, v64
	v_exp_f32_e32 v52, v52
	s_nop 0
	v_add_f32_e32 v52, 1.0, v52
	v_rcp_f32_e32 v52, v52
	s_nop 0
	v_mul_f32_e32 v52, v52, v64
	v_mul_f32_e32 v14, v52, v14
	v_mul_f32_e32 v52, 0xbfb8aa3b, v65
	v_exp_f32_e32 v52, v52
	v_cvt_pk_bf16_f32 v14, v14, s0
	v_add_f32_e32 v52, 1.0, v52
	v_rcp_f32_e32 v52, v52
	s_nop 0
	v_mul_f32_e32 v52, v52, v65
	v_mul_f32_e32 v15, v52, v15
	v_cvt_pk_bf16_f32 v15, v15, s0
	s_branch .LBB0_1555
